# G + SwiGLU epilogue rewritten: batched exp/rcp scheduling without s_nop bubbles, scalar f32 muls instead of packed (same f32 math, same association)
# speedup vs baseline: 1.0034x; 1.0029x over previous
; __device__ __forceinline__ unsigned cvt_pk_bf16(float lo, float hi) { const pk_f2_t v = {lo, hi}; return __builtin_bit_cast(unsigned, __builtin_convertvector(v, pk_bf2_t)); }
; __device__ __forceinline__ float silu_f(float g) { return g * __builtin_amdgcn_rcpf(1.0f + __builtin_amdgcn_exp2f(-1.4426950408889634f * g)); }
;     __device__ __forceinline__ void operator()(const pg8::f32x4 (&acc)[2][2][4][2], const pg8::Unit& u, int wr, int wc, int fr, int fq) const {
;         const int row0 = u.pm * 256 + wr * 64 + fr, col0 = u.pn * 128 + wc * 32 + 8 * fq;
;         bf16* base = O + (size_t)row0 * FF + col0;
; #pragma unroll
;         for (int ai = 0; ai < 2; ++ai)
; #pragma unroll
;             for (int m = 0; m < 4; ++m) {
;                 pg8::u32x4 w;
;                 { const pg8::f32x4 g = acc[ai][0][m][0], uu = acc[ai][1][m][0];
;                   w.x = pg8::cvt_pk_bf16(silu_f(g[0]) * uu[0], silu_f(g[1]) * uu[1]); w.y = pg8::cvt_pk_bf16(silu_f(g[2]) * uu[2], silu_f(g[3]) * uu[3]); }
;                 { const pg8::f32x4 g = acc[ai][0][m][1], uu = acc[ai][1][m][1];
;                   w.z = pg8::cvt_pk_bf16(silu_f(g[0]) * uu[0], silu_f(g[1]) * uu[1]); w.w = pg8::cvt_pk_bf16(silu_f(g[2]) * uu[2], silu_f(g[3]) * uu[3]); }
;                 *(pg8::u32x4*)(base + (size_t)(ai * 128 + m * 16) * FF) = w;
;                 asm volatile("" ::: "memory");
;             }
.LBB0_282:
	v_lshl_add_u32 v141, s27, 8, v142
	v_lshl_or_b32 v140, s26, 7, v144
	v_mov_b64_e32 v[146:147], s[6:7]
	v_mad_i64_i32 v[146:147], s[18:19], v141, s61, v[146:147]
	v_ashrrev_i32_e32 v141, 31, v140
	v_lshl_add_u64 v[140:141], v[140:141], 1, v[146:147]
	s_mov_b64 s[18:19], -1
	v_mul_f32_e32 v150, 0xbfb8aa3b, v126
	v_mul_f32_e32 v151, 0xbfb8aa3b, v127
	v_mul_f32_e32 v152, 0xbfb8aa3b, v128
	v_mul_f32_e32 v153, 0xbfb8aa3b, v129
	v_mul_f32_e32 v154, 0xbfb8aa3b, v118
	v_mul_f32_e32 v155, 0xbfb8aa3b, v119
	v_mul_f32_e32 v156, 0xbfb8aa3b, v120
	v_mul_f32_e32 v157, 0xbfb8aa3b, v121
	v_exp_f32_e32 v150, v150
	v_exp_f32_e32 v151, v151
	v_exp_f32_e32 v152, v152
	v_exp_f32_e32 v153, v153
	v_exp_f32_e32 v154, v154
	v_exp_f32_e32 v155, v155
	v_exp_f32_e32 v156, v156
	v_exp_f32_e32 v157, v157
	v_add_f32_e32 v150, 1.0, v150
	v_add_f32_e32 v151, 1.0, v151
	v_add_f32_e32 v152, 1.0, v152
	v_add_f32_e32 v153, 1.0, v153
	v_add_f32_e32 v154, 1.0, v154
	v_add_f32_e32 v155, 1.0, v155
	v_add_f32_e32 v156, 1.0, v156
	v_add_f32_e32 v157, 1.0, v157
	v_rcp_f32_e32 v150, v150
	v_rcp_f32_e32 v151, v151
	v_rcp_f32_e32 v152, v152
	v_rcp_f32_e32 v153, v153
	v_rcp_f32_e32 v154, v154
	v_rcp_f32_e32 v155, v155
	v_rcp_f32_e32 v156, v156
	v_rcp_f32_e32 v157, v157
	v_mul_f32_e32 v150, v126, v150
	v_mul_f32_e32 v151, v127, v151
	v_mul_f32_e32 v152, v128, v152
	v_mul_f32_e32 v153, v129, v153
	v_mul_f32_e32 v154, v118, v154
	v_mul_f32_e32 v155, v119, v155
	v_mul_f32_e32 v156, v120, v156
	v_mul_f32_e32 v157, v121, v157
	v_mul_f32_e32 v122, v150, v122
	v_mul_f32_e32 v123, v151, v123
	v_mul_f32_e32 v124, v152, v124
	v_mul_f32_e32 v125, v153, v125
	v_mul_f32_e32 v114, v154, v114
	v_mul_f32_e32 v115, v155, v115
	v_mul_f32_e32 v116, v156, v116
	v_mul_f32_e32 v117, v157, v117
	v_cvt_pk_bf16_f32 v122, v122, v123
	v_cvt_pk_bf16_f32 v123, v124, v125
	v_cvt_pk_bf16_f32 v124, v114, v115
	v_cvt_pk_bf16_f32 v125, v116, v117
	flat_store_dwordx4 v[140:141], v[122:125]
	v_mul_f32_e32 v158, 0xbfb8aa3b, v110
	v_mul_f32_e32 v159, 0xbfb8aa3b, v111
	v_mul_f32_e32 v160, 0xbfb8aa3b, v112
	v_mul_f32_e32 v161, 0xbfb8aa3b, v113
	v_mul_f32_e32 v162, 0xbfb8aa3b, v102
	v_mul_f32_e32 v163, 0xbfb8aa3b, v103
	v_mul_f32_e32 v164, 0xbfb8aa3b, v104
	v_mul_f32_e32 v165, 0xbfb8aa3b, v105
	v_exp_f32_e32 v158, v158
	v_exp_f32_e32 v159, v159
	v_exp_f32_e32 v160, v160
	v_exp_f32_e32 v161, v161
	v_exp_f32_e32 v162, v162
	v_exp_f32_e32 v163, v163
	v_exp_f32_e32 v164, v164
	v_exp_f32_e32 v165, v165
	v_add_co_u32_e32 v166, vcc, s62, v140
	v_add_f32_e32 v158, 1.0, v158
	v_add_f32_e32 v159, 1.0, v159
	v_add_f32_e32 v160, 1.0, v160
	v_add_f32_e32 v161, 1.0, v161
	v_add_f32_e32 v162, 1.0, v162
	v_add_f32_e32 v163, 1.0, v163
	v_add_f32_e32 v164, 1.0, v164
	v_add_f32_e32 v165, 1.0, v165
	v_addc_co_u32_e32 v167, vcc, 0, v141, vcc
	v_rcp_f32_e32 v158, v158
	v_rcp_f32_e32 v159, v159
	v_rcp_f32_e32 v160, v160
	v_rcp_f32_e32 v161, v161
	v_rcp_f32_e32 v162, v162
	v_rcp_f32_e32 v163, v163
	v_rcp_f32_e32 v164, v164
	v_rcp_f32_e32 v165, v165
	v_mul_f32_e32 v158, v110, v158
	v_mul_f32_e32 v159, v111, v159
	v_mul_f32_e32 v160, v112, v160
	v_mul_f32_e32 v161, v113, v161
	v_mul_f32_e32 v162, v102, v162
	v_mul_f32_e32 v163, v103, v163
	v_mul_f32_e32 v164, v104, v164
	v_mul_f32_e32 v165, v105, v165
	v_mul_f32_e32 v106, v158, v106
	v_mul_f32_e32 v107, v159, v107
	v_mul_f32_e32 v108, v160, v108
	v_mul_f32_e32 v109, v161, v109
	v_mul_f32_e32 v98, v162, v98
	v_mul_f32_e32 v99, v163, v99
	v_mul_f32_e32 v100, v164, v100
	v_mul_f32_e32 v101, v165, v101
	v_cvt_pk_bf16_f32 v106, v106, v107
	v_cvt_pk_bf16_f32 v107, v108, v109
	v_cvt_pk_bf16_f32 v108, v98, v99
	v_cvt_pk_bf16_f32 v109, v100, v101
	flat_store_dwordx4 v[166:167], v[106:109]
	v_mul_f32_e32 v150, 0xbfb8aa3b, v94
	v_mul_f32_e32 v151, 0xbfb8aa3b, v95
	v_mul_f32_e32 v152, 0xbfb8aa3b, v96
	v_mul_f32_e32 v153, 0xbfb8aa3b, v97
	v_mul_f32_e32 v154, 0xbfb8aa3b, v86
	v_mul_f32_e32 v155, 0xbfb8aa3b, v87
	v_mul_f32_e32 v156, 0xbfb8aa3b, v88
	v_mul_f32_e32 v157, 0xbfb8aa3b, v89
	v_exp_f32_e32 v150, v150
	v_exp_f32_e32 v151, v151
	v_exp_f32_e32 v152, v152
	v_exp_f32_e32 v153, v153
	v_exp_f32_e32 v154, v154
	v_exp_f32_e32 v155, v155
	v_exp_f32_e32 v156, v156
	v_exp_f32_e32 v157, v157
	v_add_co_u32_e32 v148, vcc, s63, v140
	v_add_f32_e32 v150, 1.0, v150
	v_add_f32_e32 v151, 1.0, v151
	v_add_f32_e32 v152, 1.0, v152
	v_add_f32_e32 v153, 1.0, v153
	v_add_f32_e32 v154, 1.0, v154
	v_add_f32_e32 v155, 1.0, v155
	v_add_f32_e32 v156, 1.0, v156
	v_add_f32_e32 v157, 1.0, v157
	v_addc_co_u32_e32 v149, vcc, 0, v141, vcc
	v_rcp_f32_e32 v150, v150
	v_rcp_f32_e32 v151, v151
	v_rcp_f32_e32 v152, v152
	v_rcp_f32_e32 v153, v153
	v_rcp_f32_e32 v154, v154
	v_rcp_f32_e32 v155, v155
	v_rcp_f32_e32 v156, v156
	v_rcp_f32_e32 v157, v157
	v_mul_f32_e32 v150, v94, v150
	v_mul_f32_e32 v151, v95, v151
	v_mul_f32_e32 v152, v96, v152
	v_mul_f32_e32 v153, v97, v153
	v_mul_f32_e32 v154, v86, v154
	v_mul_f32_e32 v155, v87, v155
	v_mul_f32_e32 v156, v88, v156
	v_mul_f32_e32 v157, v89, v157
	v_mul_f32_e32 v90, v150, v90
	v_mul_f32_e32 v91, v151, v91
	v_mul_f32_e32 v92, v152, v92
	v_mul_f32_e32 v93, v153, v93
	v_mul_f32_e32 v82, v154, v82
	v_mul_f32_e32 v83, v155, v83
	v_mul_f32_e32 v84, v156, v84
	v_mul_f32_e32 v85, v157, v85
	v_cvt_pk_bf16_f32 v90, v90, v91
	v_cvt_pk_bf16_f32 v91, v92, v93
	v_cvt_pk_bf16_f32 v92, v82, v83
	v_cvt_pk_bf16_f32 v93, v84, v85
	flat_store_dwordx4 v[148:149], v[90:93]
	v_mul_f32_e32 v158, 0xbfb8aa3b, v78
	v_mul_f32_e32 v159, 0xbfb8aa3b, v79
	v_mul_f32_e32 v160, 0xbfb8aa3b, v80
	v_mul_f32_e32 v161, 0xbfb8aa3b, v81
	v_mul_f32_e32 v162, 0xbfb8aa3b, v70
	v_mul_f32_e32 v163, 0xbfb8aa3b, v71
	v_mul_f32_e32 v164, 0xbfb8aa3b, v72
; __device__ __forceinline__ unsigned cvt_pk_bf16(float lo, float hi) { const pk_f2_t v = {lo, hi}; return __builtin_bit_cast(unsigned, __builtin_convertvector(v, pk_bf2_t)); }
; __device__ __forceinline__ float silu_f(float g) { return g * __builtin_amdgcn_rcpf(1.0f + __builtin_amdgcn_exp2f(-1.4426950408889634f * g)); }
;     __device__ __forceinline__ void operator()(const pg8::f32x4 (&acc)[2][2][4][2], const pg8::Unit& u, int wr, int wc, int fr, int fq) const {
;     ...
;                 { const pg8::f32x4 g = acc[ai][0][m][0], uu = acc[ai][1][m][0];
;                   w.x = pg8::cvt_pk_bf16(silu_f(g[0]) * uu[0], silu_f(g[1]) * uu[1]); w.y = pg8::cvt_pk_bf16(silu_f(g[2]) * uu[2], silu_f(g[3]) * uu[3]); }
;                 { const pg8::f32x4 g = acc[ai][0][m][1], uu = acc[ai][1][m][1];
;                   w.z = pg8::cvt_pk_bf16(silu_f(g[0]) * uu[0], silu_f(g[1]) * uu[1]); w.w = pg8::cvt_pk_bf16(silu_f(g[2]) * uu[2], silu_f(g[3]) * uu[3]); }
;                 *(pg8::u32x4*)(base + (size_t)(ai * 128 + m * 16) * FF) = w;
	v_mul_f32_e32 v165, 0xbfb8aa3b, v73
	v_exp_f32_e32 v158, v158
	v_exp_f32_e32 v159, v159
	v_exp_f32_e32 v160, v160
	v_exp_f32_e32 v161, v161
	v_exp_f32_e32 v162, v162
	v_exp_f32_e32 v163, v163
	v_exp_f32_e32 v164, v164
	v_exp_f32_e32 v165, v165
	v_add_co_u32_e32 v166, vcc, s70, v140
	v_add_f32_e32 v158, 1.0, v158
	v_add_f32_e32 v159, 1.0, v159
	v_add_f32_e32 v160, 1.0, v160
	v_add_f32_e32 v161, 1.0, v161
	v_add_f32_e32 v162, 1.0, v162
	v_add_f32_e32 v163, 1.0, v163
	v_add_f32_e32 v164, 1.0, v164
	v_add_f32_e32 v165, 1.0, v165
	v_addc_co_u32_e32 v167, vcc, 0, v141, vcc
	v_rcp_f32_e32 v158, v158
	v_rcp_f32_e32 v159, v159
	v_rcp_f32_e32 v160, v160
	v_rcp_f32_e32 v161, v161
	v_rcp_f32_e32 v162, v162
	v_rcp_f32_e32 v163, v163
	v_rcp_f32_e32 v164, v164
	v_rcp_f32_e32 v165, v165
	v_mul_f32_e32 v158, v78, v158
	v_mul_f32_e32 v159, v79, v159
	v_mul_f32_e32 v160, v80, v160
	v_mul_f32_e32 v161, v81, v161
	v_mul_f32_e32 v162, v70, v162
	v_mul_f32_e32 v163, v71, v163
	v_mul_f32_e32 v164, v72, v164
	v_mul_f32_e32 v165, v73, v165
	v_mul_f32_e32 v74, v158, v74
	v_mul_f32_e32 v75, v159, v75
	v_mul_f32_e32 v76, v160, v76
	v_mul_f32_e32 v77, v161, v77
	v_mul_f32_e32 v66, v162, v66
	v_mul_f32_e32 v67, v163, v67
	v_mul_f32_e32 v68, v164, v68
	v_mul_f32_e32 v69, v165, v69
	v_cvt_pk_bf16_f32 v74, v74, v75
	v_cvt_pk_bf16_f32 v75, v76, v77
	v_cvt_pk_bf16_f32 v76, v66, v67
	v_cvt_pk_bf16_f32 v77, v68, v69
	flat_store_dwordx4 v[166:167], v[74:77]
	v_mul_f32_e32 v150, 0xbfb8aa3b, v62
	v_mul_f32_e32 v151, 0xbfb8aa3b, v63
	v_mul_f32_e32 v152, 0xbfb8aa3b, v64
	v_mul_f32_e32 v153, 0xbfb8aa3b, v65
	v_mul_f32_e32 v154, 0xbfb8aa3b, v54
	v_mul_f32_e32 v155, 0xbfb8aa3b, v55
	v_mul_f32_e32 v156, 0xbfb8aa3b, v56
	v_mul_f32_e32 v157, 0xbfb8aa3b, v57
	v_exp_f32_e32 v150, v150
	v_exp_f32_e32 v151, v151
	v_exp_f32_e32 v152, v152
	v_exp_f32_e32 v153, v153
	v_exp_f32_e32 v154, v154
	v_exp_f32_e32 v155, v155
	v_exp_f32_e32 v156, v156
	v_exp_f32_e32 v157, v157
	v_add_co_u32_e32 v148, vcc, s3, v140
	v_add_f32_e32 v150, 1.0, v150
	v_add_f32_e32 v151, 1.0, v151
	v_add_f32_e32 v152, 1.0, v152
	v_add_f32_e32 v153, 1.0, v153
	v_add_f32_e32 v154, 1.0, v154
	v_add_f32_e32 v155, 1.0, v155
	v_add_f32_e32 v156, 1.0, v156
	v_add_f32_e32 v157, 1.0, v157
	v_addc_co_u32_e32 v149, vcc, 0, v141, vcc
	v_rcp_f32_e32 v150, v150
	v_rcp_f32_e32 v151, v151
	v_rcp_f32_e32 v152, v152
	v_rcp_f32_e32 v153, v153
	v_rcp_f32_e32 v154, v154
	v_rcp_f32_e32 v155, v155
	v_rcp_f32_e32 v156, v156
	v_rcp_f32_e32 v157, v157
	v_mul_f32_e32 v150, v62, v150
	v_mul_f32_e32 v151, v63, v151
	v_mul_f32_e32 v152, v64, v152
	v_mul_f32_e32 v153, v65, v153
	v_mul_f32_e32 v154, v54, v154
	v_mul_f32_e32 v155, v55, v155
	v_mul_f32_e32 v156, v56, v156
	v_mul_f32_e32 v157, v57, v157
	v_mul_f32_e32 v58, v150, v58
	v_mul_f32_e32 v59, v151, v59
	v_mul_f32_e32 v60, v152, v60
	v_mul_f32_e32 v61, v153, v61
	v_mul_f32_e32 v50, v154, v50
	v_mul_f32_e32 v51, v155, v51
	v_mul_f32_e32 v52, v156, v52
	v_mul_f32_e32 v53, v157, v53
	v_cvt_pk_bf16_f32 v58, v58, v59
	v_cvt_pk_bf16_f32 v59, v60, v61
	v_cvt_pk_bf16_f32 v60, v50, v51
	v_cvt_pk_bf16_f32 v61, v52, v53
	flat_store_dwordx4 v[148:149], v[58:61]
	v_mul_f32_e32 v158, 0xbfb8aa3b, v46
	v_mul_f32_e32 v159, 0xbfb8aa3b, v47
	v_mul_f32_e32 v160, 0xbfb8aa3b, v48
	v_mul_f32_e32 v161, 0xbfb8aa3b, v49
	v_mul_f32_e32 v162, 0xbfb8aa3b, v38
	v_mul_f32_e32 v163, 0xbfb8aa3b, v39
	v_mul_f32_e32 v164, 0xbfb8aa3b, v40
	v_mul_f32_e32 v165, 0xbfb8aa3b, v41
	v_exp_f32_e32 v158, v158
	v_exp_f32_e32 v159, v159
	v_exp_f32_e32 v160, v160
	v_exp_f32_e32 v161, v161
	v_exp_f32_e32 v162, v162
	v_exp_f32_e32 v163, v163
	v_exp_f32_e32 v164, v164
	v_exp_f32_e32 v165, v165
	v_add_co_u32_e32 v166, vcc, s71, v140
	v_add_f32_e32 v158, 1.0, v158
	v_add_f32_e32 v159, 1.0, v159
	v_add_f32_e32 v160, 1.0, v160
	v_add_f32_e32 v161, 1.0, v161
	v_add_f32_e32 v162, 1.0, v162
	v_add_f32_e32 v163, 1.0, v163
	v_add_f32_e32 v164, 1.0, v164
	v_add_f32_e32 v165, 1.0, v165
	v_addc_co_u32_e32 v167, vcc, 0, v141, vcc
	v_rcp_f32_e32 v158, v158
	v_rcp_f32_e32 v159, v159
	v_rcp_f32_e32 v160, v160
	v_rcp_f32_e32 v161, v161
	v_rcp_f32_e32 v162, v162
	v_rcp_f32_e32 v163, v163
	v_rcp_f32_e32 v164, v164
	v_rcp_f32_e32 v165, v165
; __device__ __forceinline__ unsigned cvt_pk_bf16(float lo, float hi) { const pk_f2_t v = {lo, hi}; return __builtin_bit_cast(unsigned, __builtin_convertvector(v, pk_bf2_t)); }
; __device__ __forceinline__ float silu_f(float g) { return g * __builtin_amdgcn_rcpf(1.0f + __builtin_amdgcn_exp2f(-1.4426950408889634f * g)); }
;     __device__ __forceinline__ void operator()(const pg8::f32x4 (&acc)[2][2][4][2], const pg8::Unit& u, int wr, int wc, int fr, int fq) const {
;     ...
;                 { const pg8::f32x4 g = acc[ai][0][m][0], uu = acc[ai][1][m][0];
;                   w.x = pg8::cvt_pk_bf16(silu_f(g[0]) * uu[0], silu_f(g[1]) * uu[1]); w.y = pg8::cvt_pk_bf16(silu_f(g[2]) * uu[2], silu_f(g[3]) * uu[3]); }
;                 { const pg8::f32x4 g = acc[ai][0][m][1], uu = acc[ai][1][m][1];
;                   w.z = pg8::cvt_pk_bf16(silu_f(g[0]) * uu[0], silu_f(g[1]) * uu[1]); w.w = pg8::cvt_pk_bf16(silu_f(g[2]) * uu[2], silu_f(g[3]) * uu[3]); }
;                 *(pg8::u32x4*)(base + (size_t)(ai * 128 + m * 16) * FF) = w;
	v_mul_f32_e32 v158, v46, v158
	v_mul_f32_e32 v159, v47, v159
	v_mul_f32_e32 v160, v48, v160
	v_mul_f32_e32 v161, v49, v161
	v_mul_f32_e32 v162, v38, v162
	v_mul_f32_e32 v163, v39, v163
	v_mul_f32_e32 v164, v40, v164
	v_mul_f32_e32 v165, v41, v165
	v_mul_f32_e32 v42, v158, v42
	v_mul_f32_e32 v43, v159, v43
	v_mul_f32_e32 v44, v160, v44
	v_mul_f32_e32 v45, v161, v45
	v_mul_f32_e32 v34, v162, v34
	v_mul_f32_e32 v35, v163, v35
	v_mul_f32_e32 v36, v164, v36
	v_mul_f32_e32 v37, v165, v37
	v_cvt_pk_bf16_f32 v42, v42, v43
	v_cvt_pk_bf16_f32 v43, v44, v45
	v_cvt_pk_bf16_f32 v44, v34, v35
	v_cvt_pk_bf16_f32 v45, v36, v37
	flat_store_dwordx4 v[166:167], v[42:45]
	v_mul_f32_e32 v150, 0xbfb8aa3b, v30
	v_mul_f32_e32 v151, 0xbfb8aa3b, v31
	v_mul_f32_e32 v152, 0xbfb8aa3b, v32
	v_mul_f32_e32 v153, 0xbfb8aa3b, v33
	v_mul_f32_e32 v154, 0xbfb8aa3b, v22
	v_mul_f32_e32 v155, 0xbfb8aa3b, v23
	v_mul_f32_e32 v156, 0xbfb8aa3b, v24
	v_mul_f32_e32 v157, 0xbfb8aa3b, v25
	v_exp_f32_e32 v150, v150
	v_exp_f32_e32 v151, v151
	v_exp_f32_e32 v152, v152
	v_exp_f32_e32 v153, v153
	v_exp_f32_e32 v154, v154
	v_exp_f32_e32 v155, v155
	v_exp_f32_e32 v156, v156
	v_exp_f32_e32 v157, v157
	v_add_co_u32_e32 v148, vcc, s72, v140
	v_add_f32_e32 v150, 1.0, v150
	v_add_f32_e32 v151, 1.0, v151
	v_add_f32_e32 v152, 1.0, v152
	v_add_f32_e32 v153, 1.0, v153
	v_add_f32_e32 v154, 1.0, v154
	v_add_f32_e32 v155, 1.0, v155
	v_add_f32_e32 v156, 1.0, v156
	v_add_f32_e32 v157, 1.0, v157
	v_addc_co_u32_e32 v149, vcc, 0, v141, vcc
	v_rcp_f32_e32 v150, v150
	v_rcp_f32_e32 v151, v151
	v_rcp_f32_e32 v152, v152
	v_rcp_f32_e32 v153, v153
	v_rcp_f32_e32 v154, v154
	v_rcp_f32_e32 v155, v155
	v_rcp_f32_e32 v156, v156
	v_rcp_f32_e32 v157, v157
	v_mul_f32_e32 v150, v30, v150
	v_mul_f32_e32 v151, v31, v151
	v_mul_f32_e32 v152, v32, v152
	v_mul_f32_e32 v153, v33, v153
	v_mul_f32_e32 v154, v22, v154
	v_mul_f32_e32 v155, v23, v155
	v_mul_f32_e32 v156, v24, v156
	v_mul_f32_e32 v157, v25, v157
	v_mul_f32_e32 v26, v150, v26
	v_mul_f32_e32 v27, v151, v27
	v_mul_f32_e32 v28, v152, v28
	v_mul_f32_e32 v29, v153, v29
	v_mul_f32_e32 v18, v154, v18
	v_mul_f32_e32 v19, v155, v19
	v_mul_f32_e32 v20, v156, v20
	v_mul_f32_e32 v21, v157, v21
	v_cvt_pk_bf16_f32 v26, v26, v27
	v_cvt_pk_bf16_f32 v27, v28, v29
	v_cvt_pk_bf16_f32 v28, v18, v19
	v_cvt_pk_bf16_f32 v29, v20, v21
	flat_store_dwordx4 v[148:149], v[26:29]
	v_mul_f32_e32 v158, 0xbfb8aa3b, v14
	v_mul_f32_e32 v159, 0xbfb8aa3b, v15
	v_mul_f32_e32 v160, 0xbfb8aa3b, v16
	v_mul_f32_e32 v161, 0xbfb8aa3b, v17
	v_mul_f32_e32 v162, 0xbfb8aa3b, v6
	v_mul_f32_e32 v163, 0xbfb8aa3b, v7
	v_mul_f32_e32 v164, 0xbfb8aa3b, v8
	v_mul_f32_e32 v165, 0xbfb8aa3b, v9
	v_exp_f32_e32 v158, v158
	v_exp_f32_e32 v159, v159
	v_exp_f32_e32 v160, v160
	v_exp_f32_e32 v161, v161
	v_exp_f32_e32 v162, v162
	v_exp_f32_e32 v163, v163
	v_exp_f32_e32 v164, v164
	v_exp_f32_e32 v165, v165
	v_add_co_u32_e32 v166, vcc, 0x1e4000, v140
	v_add_f32_e32 v158, 1.0, v158
	v_add_f32_e32 v159, 1.0, v159
	v_add_f32_e32 v160, 1.0, v160
	v_add_f32_e32 v161, 1.0, v161
	v_add_f32_e32 v162, 1.0, v162
	v_add_f32_e32 v163, 1.0, v163
	v_add_f32_e32 v164, 1.0, v164
	v_add_f32_e32 v165, 1.0, v165
	v_addc_co_u32_e32 v167, vcc, 0, v141, vcc
	v_rcp_f32_e32 v158, v158
	v_rcp_f32_e32 v159, v159
	v_rcp_f32_e32 v160, v160
	v_rcp_f32_e32 v161, v161
	v_rcp_f32_e32 v162, v162
	v_rcp_f32_e32 v163, v163
	v_rcp_f32_e32 v164, v164
	v_rcp_f32_e32 v165, v165
	v_mul_f32_e32 v158, v14, v158
	v_mul_f32_e32 v159, v15, v159
	v_mul_f32_e32 v160, v16, v160
	v_mul_f32_e32 v161, v17, v161
	v_mul_f32_e32 v162, v6, v162
	v_mul_f32_e32 v163, v7, v163
	v_mul_f32_e32 v164, v8, v164
	v_mul_f32_e32 v165, v9, v165
	v_mul_f32_e32 v10, v158, v10
	v_mul_f32_e32 v11, v159, v11
	v_mul_f32_e32 v12, v160, v12
	v_mul_f32_e32 v13, v161, v13
	v_mul_f32_e32 v2, v162, v2
	v_mul_f32_e32 v3, v163, v3
	v_mul_f32_e32 v4, v164, v4
	v_mul_f32_e32 v5, v165, v5
	v_cvt_pk_bf16_f32 v10, v10, v11
	v_cvt_pk_bf16_f32 v11, v12, v13
	v_cvt_pk_bf16_f32 v12, v2, v3
	v_cvt_pk_bf16_f32 v13, v4, v5
	flat_store_dwordx4 v[166:167], v[10:13]
	s_andn2_b64 vcc, exec, s[38:39]
	s_cbranch_vccnz .LBB0_275
	s_andn2_b64 vcc, exec, s[0:1]
	s_cbranch_vccnz .LBB0_274
	s_barrier
	s_branch .LBB0_274

; __device__ __forceinline__ unsigned cvt_pk_bf16(float lo, float hi) { const pk_f2_t v = {lo, hi}; return __builtin_bit_cast(unsigned, __builtin_convertvector(v, pk_bf2_t)); }
; __device__ __forceinline__ float silu_f(float g) { return g * __builtin_amdgcn_rcpf(1.0f + __builtin_amdgcn_exp2f(-1.4426950408889634f * g)); }
;     __device__ __forceinline__ void operator()(const pg8::f32x4 (&acc)[2][2][4][2], const pg8::Unit& u, int wr, int wc, int fr, int fq) const {
;         const int row0 = u.pm * 256 + wr * 64 + fr, col0 = u.pn * 128 + wc * 32 + 8 * fq;
;         bf16* base = O + (size_t)row0 * FF + col0;
; #pragma unroll
;         for (int ai = 0; ai < 2; ++ai)
; #pragma unroll
;             for (int m = 0; m < 4; ++m) {
;                 pg8::u32x4 w;
;                 { const pg8::f32x4 g = acc[ai][0][m][0], uu = acc[ai][1][m][0];
;                   w.x = pg8::cvt_pk_bf16(silu_f(g[0]) * uu[0], silu_f(g[1]) * uu[1]); w.y = pg8::cvt_pk_bf16(silu_f(g[2]) * uu[2], silu_f(g[3]) * uu[3]); }
;                 { const pg8::f32x4 g = acc[ai][0][m][1], uu = acc[ai][1][m][1];
;                   w.z = pg8::cvt_pk_bf16(silu_f(g[0]) * uu[0], silu_f(g[1]) * uu[1]); w.w = pg8::cvt_pk_bf16(silu_f(g[2]) * uu[2], silu_f(g[3]) * uu[3]); }
;                 *(pg8::u32x4*)(base + (size_t)(ai * 128 + m * 16) * FF) = w;
.LBB0_1800:
	v_lshl_add_u32 v141, s27, 8, v142
	v_lshl_or_b32 v140, s26, 7, v144
	v_mov_b64_e32 v[146:147], s[6:7]
	v_mad_i64_i32 v[146:147], s[18:19], v141, s61, v[146:147]
	v_ashrrev_i32_e32 v141, 31, v140
	v_lshl_add_u64 v[140:141], v[140:141], 1, v[146:147]
	s_mov_b64 s[18:19], -1
	v_mul_f32_e32 v150, 0xbfb8aa3b, v126
	v_mul_f32_e32 v151, 0xbfb8aa3b, v127
	v_mul_f32_e32 v152, 0xbfb8aa3b, v128
	v_mul_f32_e32 v153, 0xbfb8aa3b, v129
	v_mul_f32_e32 v154, 0xbfb8aa3b, v118
	v_mul_f32_e32 v155, 0xbfb8aa3b, v119
	v_mul_f32_e32 v156, 0xbfb8aa3b, v120
	v_mul_f32_e32 v157, 0xbfb8aa3b, v121
	v_exp_f32_e32 v150, v150
	v_exp_f32_e32 v151, v151
	v_exp_f32_e32 v152, v152
	v_exp_f32_e32 v153, v153
	v_exp_f32_e32 v154, v154
	v_exp_f32_e32 v155, v155
	v_exp_f32_e32 v156, v156
	v_exp_f32_e32 v157, v157
	v_add_f32_e32 v150, 1.0, v150
	v_add_f32_e32 v151, 1.0, v151
	v_add_f32_e32 v152, 1.0, v152
	v_add_f32_e32 v153, 1.0, v153
	v_add_f32_e32 v154, 1.0, v154
	v_add_f32_e32 v155, 1.0, v155
	v_add_f32_e32 v156, 1.0, v156
	v_add_f32_e32 v157, 1.0, v157
	v_rcp_f32_e32 v150, v150
	v_rcp_f32_e32 v151, v151
	v_rcp_f32_e32 v152, v152
	v_rcp_f32_e32 v153, v153
	v_rcp_f32_e32 v154, v154
	v_rcp_f32_e32 v155, v155
	v_rcp_f32_e32 v156, v156
	v_rcp_f32_e32 v157, v157
	v_mul_f32_e32 v150, v126, v150
	v_mul_f32_e32 v151, v127, v151
	v_mul_f32_e32 v152, v128, v152
	v_mul_f32_e32 v153, v129, v153
	v_mul_f32_e32 v154, v118, v154
	v_mul_f32_e32 v155, v119, v155
	v_mul_f32_e32 v156, v120, v156
	v_mul_f32_e32 v157, v121, v157
	v_mul_f32_e32 v122, v150, v122
	v_mul_f32_e32 v123, v151, v123
	v_mul_f32_e32 v124, v152, v124
	v_mul_f32_e32 v125, v153, v125
	v_mul_f32_e32 v114, v154, v114
	v_mul_f32_e32 v115, v155, v115
	v_mul_f32_e32 v116, v156, v116
	v_mul_f32_e32 v117, v157, v117
	v_cvt_pk_bf16_f32 v122, v122, v123
	v_cvt_pk_bf16_f32 v123, v124, v125
	v_cvt_pk_bf16_f32 v124, v114, v115
	v_cvt_pk_bf16_f32 v125, v116, v117
	flat_store_dwordx4 v[140:141], v[122:125]
	v_mul_f32_e32 v158, 0xbfb8aa3b, v110
	v_mul_f32_e32 v159, 0xbfb8aa3b, v111
	v_mul_f32_e32 v160, 0xbfb8aa3b, v112
	v_mul_f32_e32 v161, 0xbfb8aa3b, v113
	v_mul_f32_e32 v162, 0xbfb8aa3b, v102
	v_mul_f32_e32 v163, 0xbfb8aa3b, v103
	v_mul_f32_e32 v164, 0xbfb8aa3b, v104
	v_mul_f32_e32 v165, 0xbfb8aa3b, v105
	v_exp_f32_e32 v158, v158
	v_exp_f32_e32 v159, v159
	v_exp_f32_e32 v160, v160
	v_exp_f32_e32 v161, v161
	v_exp_f32_e32 v162, v162
	v_exp_f32_e32 v163, v163
	v_exp_f32_e32 v164, v164
	v_exp_f32_e32 v165, v165
	v_add_co_u32_e32 v166, vcc, s62, v140
	v_add_f32_e32 v158, 1.0, v158
	v_add_f32_e32 v159, 1.0, v159
	v_add_f32_e32 v160, 1.0, v160
	v_add_f32_e32 v161, 1.0, v161
	v_add_f32_e32 v162, 1.0, v162
	v_add_f32_e32 v163, 1.0, v163
	v_add_f32_e32 v164, 1.0, v164
	v_add_f32_e32 v165, 1.0, v165
	v_addc_co_u32_e32 v167, vcc, 0, v141, vcc
	v_rcp_f32_e32 v158, v158
	v_rcp_f32_e32 v159, v159
	v_rcp_f32_e32 v160, v160
	v_rcp_f32_e32 v161, v161
	v_rcp_f32_e32 v162, v162
	v_rcp_f32_e32 v163, v163
	v_rcp_f32_e32 v164, v164
	v_rcp_f32_e32 v165, v165
	v_mul_f32_e32 v158, v110, v158
	v_mul_f32_e32 v159, v111, v159
	v_mul_f32_e32 v160, v112, v160
	v_mul_f32_e32 v161, v113, v161
	v_mul_f32_e32 v162, v102, v162
	v_mul_f32_e32 v163, v103, v163
	v_mul_f32_e32 v164, v104, v164
	v_mul_f32_e32 v165, v105, v165
	v_mul_f32_e32 v106, v158, v106
	v_mul_f32_e32 v107, v159, v107
	v_mul_f32_e32 v108, v160, v108
	v_mul_f32_e32 v109, v161, v109
	v_mul_f32_e32 v98, v162, v98
	v_mul_f32_e32 v99, v163, v99
	v_mul_f32_e32 v100, v164, v100
	v_mul_f32_e32 v101, v165, v101
	v_cvt_pk_bf16_f32 v106, v106, v107
	v_cvt_pk_bf16_f32 v107, v108, v109
	v_cvt_pk_bf16_f32 v108, v98, v99
	v_cvt_pk_bf16_f32 v109, v100, v101
	flat_store_dwordx4 v[166:167], v[106:109]
	v_mul_f32_e32 v150, 0xbfb8aa3b, v94
	v_mul_f32_e32 v151, 0xbfb8aa3b, v95
	v_mul_f32_e32 v152, 0xbfb8aa3b, v96
	v_mul_f32_e32 v153, 0xbfb8aa3b, v97
	v_mul_f32_e32 v154, 0xbfb8aa3b, v86
	v_mul_f32_e32 v155, 0xbfb8aa3b, v87
	v_mul_f32_e32 v156, 0xbfb8aa3b, v88
	v_mul_f32_e32 v157, 0xbfb8aa3b, v89
	v_exp_f32_e32 v150, v150
	v_exp_f32_e32 v151, v151
	v_exp_f32_e32 v152, v152
	v_exp_f32_e32 v153, v153
	v_exp_f32_e32 v154, v154
	v_exp_f32_e32 v155, v155
	v_exp_f32_e32 v156, v156
	v_exp_f32_e32 v157, v157
	v_add_co_u32_e32 v148, vcc, s63, v140
	v_add_f32_e32 v150, 1.0, v150
	v_add_f32_e32 v151, 1.0, v151
	v_add_f32_e32 v152, 1.0, v152
	v_add_f32_e32 v153, 1.0, v153
	v_add_f32_e32 v154, 1.0, v154
	v_add_f32_e32 v155, 1.0, v155
	v_add_f32_e32 v156, 1.0, v156
	v_add_f32_e32 v157, 1.0, v157
	v_addc_co_u32_e32 v149, vcc, 0, v141, vcc
	v_rcp_f32_e32 v150, v150
	v_rcp_f32_e32 v151, v151
	v_rcp_f32_e32 v152, v152
	v_rcp_f32_e32 v153, v153
	v_rcp_f32_e32 v154, v154
	v_rcp_f32_e32 v155, v155
	v_rcp_f32_e32 v156, v156
	v_rcp_f32_e32 v157, v157
	v_mul_f32_e32 v150, v94, v150
	v_mul_f32_e32 v151, v95, v151
	v_mul_f32_e32 v152, v96, v152
	v_mul_f32_e32 v153, v97, v153
	v_mul_f32_e32 v154, v86, v154
	v_mul_f32_e32 v155, v87, v155
	v_mul_f32_e32 v156, v88, v156
	v_mul_f32_e32 v157, v89, v157
	v_mul_f32_e32 v90, v150, v90
	v_mul_f32_e32 v91, v151, v91
	v_mul_f32_e32 v92, v152, v92
	v_mul_f32_e32 v93, v153, v93
	v_mul_f32_e32 v82, v154, v82
	v_mul_f32_e32 v83, v155, v83
	v_mul_f32_e32 v84, v156, v84
	v_mul_f32_e32 v85, v157, v85
	v_cvt_pk_bf16_f32 v90, v90, v91
	v_cvt_pk_bf16_f32 v91, v92, v93
	v_cvt_pk_bf16_f32 v92, v82, v83
	v_cvt_pk_bf16_f32 v93, v84, v85
	flat_store_dwordx4 v[148:149], v[90:93]
	v_mul_f32_e32 v158, 0xbfb8aa3b, v78
	v_mul_f32_e32 v159, 0xbfb8aa3b, v79
	v_mul_f32_e32 v160, 0xbfb8aa3b, v80
	v_mul_f32_e32 v161, 0xbfb8aa3b, v81
	v_mul_f32_e32 v162, 0xbfb8aa3b, v70
	v_mul_f32_e32 v163, 0xbfb8aa3b, v71
	v_mul_f32_e32 v164, 0xbfb8aa3b, v72
; __device__ __forceinline__ unsigned cvt_pk_bf16(float lo, float hi) { const pk_f2_t v = {lo, hi}; return __builtin_bit_cast(unsigned, __builtin_convertvector(v, pk_bf2_t)); }
; __device__ __forceinline__ float silu_f(float g) { return g * __builtin_amdgcn_rcpf(1.0f + __builtin_amdgcn_exp2f(-1.4426950408889634f * g)); }
;     __device__ __forceinline__ void operator()(const pg8::f32x4 (&acc)[2][2][4][2], const pg8::Unit& u, int wr, int wc, int fr, int fq) const {
;     ...
;                 { const pg8::f32x4 g = acc[ai][0][m][0], uu = acc[ai][1][m][0];
;                   w.x = pg8::cvt_pk_bf16(silu_f(g[0]) * uu[0], silu_f(g[1]) * uu[1]); w.y = pg8::cvt_pk_bf16(silu_f(g[2]) * uu[2], silu_f(g[3]) * uu[3]); }
;                 { const pg8::f32x4 g = acc[ai][0][m][1], uu = acc[ai][1][m][1];
;                   w.z = pg8::cvt_pk_bf16(silu_f(g[0]) * uu[0], silu_f(g[1]) * uu[1]); w.w = pg8::cvt_pk_bf16(silu_f(g[2]) * uu[2], silu_f(g[3]) * uu[3]); }
;                 *(pg8::u32x4*)(base + (size_t)(ai * 128 + m * 16) * FF) = w;
	v_mul_f32_e32 v165, 0xbfb8aa3b, v73
	v_exp_f32_e32 v158, v158
	v_exp_f32_e32 v159, v159
	v_exp_f32_e32 v160, v160
	v_exp_f32_e32 v161, v161
	v_exp_f32_e32 v162, v162
	v_exp_f32_e32 v163, v163
	v_exp_f32_e32 v164, v164
	v_exp_f32_e32 v165, v165
	v_add_co_u32_e32 v166, vcc, s70, v140
	v_add_f32_e32 v158, 1.0, v158
	v_add_f32_e32 v159, 1.0, v159
	v_add_f32_e32 v160, 1.0, v160
	v_add_f32_e32 v161, 1.0, v161
	v_add_f32_e32 v162, 1.0, v162
	v_add_f32_e32 v163, 1.0, v163
	v_add_f32_e32 v164, 1.0, v164
	v_add_f32_e32 v165, 1.0, v165
	v_addc_co_u32_e32 v167, vcc, 0, v141, vcc
	v_rcp_f32_e32 v158, v158
	v_rcp_f32_e32 v159, v159
	v_rcp_f32_e32 v160, v160
	v_rcp_f32_e32 v161, v161
	v_rcp_f32_e32 v162, v162
	v_rcp_f32_e32 v163, v163
	v_rcp_f32_e32 v164, v164
	v_rcp_f32_e32 v165, v165
	v_mul_f32_e32 v158, v78, v158
	v_mul_f32_e32 v159, v79, v159
	v_mul_f32_e32 v160, v80, v160
	v_mul_f32_e32 v161, v81, v161
	v_mul_f32_e32 v162, v70, v162
	v_mul_f32_e32 v163, v71, v163
	v_mul_f32_e32 v164, v72, v164
	v_mul_f32_e32 v165, v73, v165
	v_mul_f32_e32 v74, v158, v74
	v_mul_f32_e32 v75, v159, v75
	v_mul_f32_e32 v76, v160, v76
	v_mul_f32_e32 v77, v161, v77
	v_mul_f32_e32 v66, v162, v66
	v_mul_f32_e32 v67, v163, v67
	v_mul_f32_e32 v68, v164, v68
	v_mul_f32_e32 v69, v165, v69
	v_cvt_pk_bf16_f32 v74, v74, v75
	v_cvt_pk_bf16_f32 v75, v76, v77
	v_cvt_pk_bf16_f32 v76, v66, v67
	v_cvt_pk_bf16_f32 v77, v68, v69
	flat_store_dwordx4 v[166:167], v[74:77]
	v_mul_f32_e32 v150, 0xbfb8aa3b, v62
	v_mul_f32_e32 v151, 0xbfb8aa3b, v63
	v_mul_f32_e32 v152, 0xbfb8aa3b, v64
	v_mul_f32_e32 v153, 0xbfb8aa3b, v65
	v_mul_f32_e32 v154, 0xbfb8aa3b, v54
	v_mul_f32_e32 v155, 0xbfb8aa3b, v55
	v_mul_f32_e32 v156, 0xbfb8aa3b, v56
	v_mul_f32_e32 v157, 0xbfb8aa3b, v57
	v_exp_f32_e32 v150, v150
	v_exp_f32_e32 v151, v151
	v_exp_f32_e32 v152, v152
	v_exp_f32_e32 v153, v153
	v_exp_f32_e32 v154, v154
	v_exp_f32_e32 v155, v155
	v_exp_f32_e32 v156, v156
	v_exp_f32_e32 v157, v157
	v_add_co_u32_e32 v148, vcc, s3, v140
	v_add_f32_e32 v150, 1.0, v150
	v_add_f32_e32 v151, 1.0, v151
	v_add_f32_e32 v152, 1.0, v152
	v_add_f32_e32 v153, 1.0, v153
	v_add_f32_e32 v154, 1.0, v154
	v_add_f32_e32 v155, 1.0, v155
	v_add_f32_e32 v156, 1.0, v156
	v_add_f32_e32 v157, 1.0, v157
	v_addc_co_u32_e32 v149, vcc, 0, v141, vcc
	v_rcp_f32_e32 v150, v150
	v_rcp_f32_e32 v151, v151
	v_rcp_f32_e32 v152, v152
	v_rcp_f32_e32 v153, v153
	v_rcp_f32_e32 v154, v154
	v_rcp_f32_e32 v155, v155
	v_rcp_f32_e32 v156, v156
	v_rcp_f32_e32 v157, v157
	v_mul_f32_e32 v150, v62, v150
	v_mul_f32_e32 v151, v63, v151
	v_mul_f32_e32 v152, v64, v152
	v_mul_f32_e32 v153, v65, v153
	v_mul_f32_e32 v154, v54, v154
	v_mul_f32_e32 v155, v55, v155
	v_mul_f32_e32 v156, v56, v156
	v_mul_f32_e32 v157, v57, v157
	v_mul_f32_e32 v58, v150, v58
	v_mul_f32_e32 v59, v151, v59
	v_mul_f32_e32 v60, v152, v60
	v_mul_f32_e32 v61, v153, v61
	v_mul_f32_e32 v50, v154, v50
	v_mul_f32_e32 v51, v155, v51
	v_mul_f32_e32 v52, v156, v52
	v_mul_f32_e32 v53, v157, v53
	v_cvt_pk_bf16_f32 v58, v58, v59
	v_cvt_pk_bf16_f32 v59, v60, v61
	v_cvt_pk_bf16_f32 v60, v50, v51
	v_cvt_pk_bf16_f32 v61, v52, v53
	flat_store_dwordx4 v[148:149], v[58:61]
	v_mul_f32_e32 v158, 0xbfb8aa3b, v46
	v_mul_f32_e32 v159, 0xbfb8aa3b, v47
	v_mul_f32_e32 v160, 0xbfb8aa3b, v48
	v_mul_f32_e32 v161, 0xbfb8aa3b, v49
	v_mul_f32_e32 v162, 0xbfb8aa3b, v38
	v_mul_f32_e32 v163, 0xbfb8aa3b, v39
	v_mul_f32_e32 v164, 0xbfb8aa3b, v40
	v_mul_f32_e32 v165, 0xbfb8aa3b, v41
	v_exp_f32_e32 v158, v158
	v_exp_f32_e32 v159, v159
	v_exp_f32_e32 v160, v160
	v_exp_f32_e32 v161, v161
	v_exp_f32_e32 v162, v162
	v_exp_f32_e32 v163, v163
	v_exp_f32_e32 v164, v164
	v_exp_f32_e32 v165, v165
	v_add_co_u32_e32 v166, vcc, s71, v140
	v_add_f32_e32 v158, 1.0, v158
	v_add_f32_e32 v159, 1.0, v159
	v_add_f32_e32 v160, 1.0, v160
	v_add_f32_e32 v161, 1.0, v161
	v_add_f32_e32 v162, 1.0, v162
	v_add_f32_e32 v163, 1.0, v163
	v_add_f32_e32 v164, 1.0, v164
	v_add_f32_e32 v165, 1.0, v165
	v_addc_co_u32_e32 v167, vcc, 0, v141, vcc
	v_rcp_f32_e32 v158, v158
	v_rcp_f32_e32 v159, v159
	v_rcp_f32_e32 v160, v160
	v_rcp_f32_e32 v161, v161
	v_rcp_f32_e32 v162, v162
	v_rcp_f32_e32 v163, v163
	v_rcp_f32_e32 v164, v164
	v_rcp_f32_e32 v165, v165
; __device__ __forceinline__ unsigned cvt_pk_bf16(float lo, float hi) { const pk_f2_t v = {lo, hi}; return __builtin_bit_cast(unsigned, __builtin_convertvector(v, pk_bf2_t)); }
; __device__ __forceinline__ float silu_f(float g) { return g * __builtin_amdgcn_rcpf(1.0f + __builtin_amdgcn_exp2f(-1.4426950408889634f * g)); }
;     __device__ __forceinline__ void operator()(const pg8::f32x4 (&acc)[2][2][4][2], const pg8::Unit& u, int wr, int wc, int fr, int fq) const {
;     ...
;                 { const pg8::f32x4 g = acc[ai][0][m][0], uu = acc[ai][1][m][0];
;                   w.x = pg8::cvt_pk_bf16(silu_f(g[0]) * uu[0], silu_f(g[1]) * uu[1]); w.y = pg8::cvt_pk_bf16(silu_f(g[2]) * uu[2], silu_f(g[3]) * uu[3]); }
;                 { const pg8::f32x4 g = acc[ai][0][m][1], uu = acc[ai][1][m][1];
;                   w.z = pg8::cvt_pk_bf16(silu_f(g[0]) * uu[0], silu_f(g[1]) * uu[1]); w.w = pg8::cvt_pk_bf16(silu_f(g[2]) * uu[2], silu_f(g[3]) * uu[3]); }
;                 *(pg8::u32x4*)(base + (size_t)(ai * 128 + m * 16) * FF) = w;
	v_mul_f32_e32 v158, v46, v158
	v_mul_f32_e32 v159, v47, v159
	v_mul_f32_e32 v160, v48, v160
	v_mul_f32_e32 v161, v49, v161
	v_mul_f32_e32 v162, v38, v162
	v_mul_f32_e32 v163, v39, v163
	v_mul_f32_e32 v164, v40, v164
	v_mul_f32_e32 v165, v41, v165
	v_mul_f32_e32 v42, v158, v42
	v_mul_f32_e32 v43, v159, v43
	v_mul_f32_e32 v44, v160, v44
	v_mul_f32_e32 v45, v161, v45
	v_mul_f32_e32 v34, v162, v34
	v_mul_f32_e32 v35, v163, v35
	v_mul_f32_e32 v36, v164, v36
	v_mul_f32_e32 v37, v165, v37
	v_cvt_pk_bf16_f32 v42, v42, v43
	v_cvt_pk_bf16_f32 v43, v44, v45
	v_cvt_pk_bf16_f32 v44, v34, v35
	v_cvt_pk_bf16_f32 v45, v36, v37
	flat_store_dwordx4 v[166:167], v[42:45]
	v_mul_f32_e32 v150, 0xbfb8aa3b, v30
	v_mul_f32_e32 v151, 0xbfb8aa3b, v31
	v_mul_f32_e32 v152, 0xbfb8aa3b, v32
	v_mul_f32_e32 v153, 0xbfb8aa3b, v33
	v_mul_f32_e32 v154, 0xbfb8aa3b, v22
	v_mul_f32_e32 v155, 0xbfb8aa3b, v23
	v_mul_f32_e32 v156, 0xbfb8aa3b, v24
	v_mul_f32_e32 v157, 0xbfb8aa3b, v25
	v_exp_f32_e32 v150, v150
	v_exp_f32_e32 v151, v151
	v_exp_f32_e32 v152, v152
	v_exp_f32_e32 v153, v153
	v_exp_f32_e32 v154, v154
	v_exp_f32_e32 v155, v155
	v_exp_f32_e32 v156, v156
	v_exp_f32_e32 v157, v157
	v_add_co_u32_e32 v148, vcc, s72, v140
	v_add_f32_e32 v150, 1.0, v150
	v_add_f32_e32 v151, 1.0, v151
	v_add_f32_e32 v152, 1.0, v152
	v_add_f32_e32 v153, 1.0, v153
	v_add_f32_e32 v154, 1.0, v154
	v_add_f32_e32 v155, 1.0, v155
	v_add_f32_e32 v156, 1.0, v156
	v_add_f32_e32 v157, 1.0, v157
	v_addc_co_u32_e32 v149, vcc, 0, v141, vcc
	v_rcp_f32_e32 v150, v150
	v_rcp_f32_e32 v151, v151
	v_rcp_f32_e32 v152, v152
	v_rcp_f32_e32 v153, v153
	v_rcp_f32_e32 v154, v154
	v_rcp_f32_e32 v155, v155
	v_rcp_f32_e32 v156, v156
	v_rcp_f32_e32 v157, v157
	v_mul_f32_e32 v150, v30, v150
	v_mul_f32_e32 v151, v31, v151
	v_mul_f32_e32 v152, v32, v152
	v_mul_f32_e32 v153, v33, v153
	v_mul_f32_e32 v154, v22, v154
	v_mul_f32_e32 v155, v23, v155
	v_mul_f32_e32 v156, v24, v156
	v_mul_f32_e32 v157, v25, v157
	v_mul_f32_e32 v26, v150, v26
	v_mul_f32_e32 v27, v151, v27
	v_mul_f32_e32 v28, v152, v28
	v_mul_f32_e32 v29, v153, v29
	v_mul_f32_e32 v18, v154, v18
	v_mul_f32_e32 v19, v155, v19
	v_mul_f32_e32 v20, v156, v20
	v_mul_f32_e32 v21, v157, v21
	v_cvt_pk_bf16_f32 v26, v26, v27
	v_cvt_pk_bf16_f32 v27, v28, v29
	v_cvt_pk_bf16_f32 v28, v18, v19
	v_cvt_pk_bf16_f32 v29, v20, v21
	flat_store_dwordx4 v[148:149], v[26:29]
	v_mul_f32_e32 v158, 0xbfb8aa3b, v14
	v_mul_f32_e32 v159, 0xbfb8aa3b, v15
	v_mul_f32_e32 v160, 0xbfb8aa3b, v16
	v_mul_f32_e32 v161, 0xbfb8aa3b, v17
	v_mul_f32_e32 v162, 0xbfb8aa3b, v6
	v_mul_f32_e32 v163, 0xbfb8aa3b, v7
	v_mul_f32_e32 v164, 0xbfb8aa3b, v8
	v_mul_f32_e32 v165, 0xbfb8aa3b, v9
	v_exp_f32_e32 v158, v158
	v_exp_f32_e32 v159, v159
	v_exp_f32_e32 v160, v160
	v_exp_f32_e32 v161, v161
	v_exp_f32_e32 v162, v162
	v_exp_f32_e32 v163, v163
	v_exp_f32_e32 v164, v164
	v_exp_f32_e32 v165, v165
	v_add_co_u32_e32 v166, vcc, 0x1e4000, v140
	v_add_f32_e32 v158, 1.0, v158
	v_add_f32_e32 v159, 1.0, v159
	v_add_f32_e32 v160, 1.0, v160
	v_add_f32_e32 v161, 1.0, v161
	v_add_f32_e32 v162, 1.0, v162
	v_add_f32_e32 v163, 1.0, v163
	v_add_f32_e32 v164, 1.0, v164
	v_add_f32_e32 v165, 1.0, v165
	v_addc_co_u32_e32 v167, vcc, 0, v141, vcc
	v_rcp_f32_e32 v158, v158
	v_rcp_f32_e32 v159, v159
	v_rcp_f32_e32 v160, v160
	v_rcp_f32_e32 v161, v161
	v_rcp_f32_e32 v162, v162
	v_rcp_f32_e32 v163, v163
	v_rcp_f32_e32 v164, v164
	v_rcp_f32_e32 v165, v165
	v_mul_f32_e32 v158, v14, v158
	v_mul_f32_e32 v159, v15, v159
	v_mul_f32_e32 v160, v16, v160
	v_mul_f32_e32 v161, v17, v161
	v_mul_f32_e32 v162, v6, v162
	v_mul_f32_e32 v163, v7, v163
	v_mul_f32_e32 v164, v8, v164
	v_mul_f32_e32 v165, v9, v165
	v_mul_f32_e32 v10, v158, v10
	v_mul_f32_e32 v11, v159, v11
	v_mul_f32_e32 v12, v160, v12
	v_mul_f32_e32 v13, v161, v13
	v_mul_f32_e32 v2, v162, v2
	v_mul_f32_e32 v3, v163, v3
	v_mul_f32_e32 v4, v164, v4
	v_mul_f32_e32 v5, v165, v5
	v_cvt_pk_bf16_f32 v10, v10, v11
	v_cvt_pk_bf16_f32 v11, v12, v13
	v_cvt_pk_bf16_f32 v12, v2, v3
	v_cvt_pk_bf16_f32 v13, v4, v5
	flat_store_dwordx4 v[166:167], v[10:13]
	s_andn2_b64 vcc, exec, s[36:37]
	s_cbranch_vccnz .LBB0_1793
	s_andn2_b64 vcc, exec, s[0:1]
	s_cbranch_vccnz .LBB0_1792
	s_barrier
	s_branch .LBB0_1792
